# P7 prologue: the 8 serialized S-fragment load rounds are preceded by one warm-up burst of the same 8 lines per lane into dead registers (rounds then hit cache); on top of v_p12_lw
# baseline (speedup 1.0000x reference)
; __device__ __forceinline__ unsigned pk2(float lo, float hi) { return f2bf(lo) | (f2bf(hi) << 16); }
; __device__ __forceinline__ void phase_scan2z(const Params& p) {
;     ...
;             for (int ks = 0; ks < 2; ++ks) { u32x4 w = (u32x4){0u, 0u, 0u, 0u};
;                 if (ch > 0) { const float* sp = ST + ((size_t)(u - 1) * 2) * 4096 + (16 * c + lr) * 64 + 32 * ks + 8 * lq; const f32x4 x0 = *(const f32x4*)sp, x1 = *(const f32x4*)(sp + 4);
;                     w.x = pk2(x0[0], x0[1]); w.y = pk2(x0[2], x0[3]); w.z = pk2(x1[0], x1[1]); w.w = pk2(x1[2], x1[3]); }
;                 Sf[c][ks] = __builtin_bit_cast(bf16x8, w); }
.LBB0_1351:
	v_ashrrev_i32_e32 v113, 31, v112
	v_lshrrev_b32_e32 v0, 26, v113
	v_add_u32_e32 v35, v112, v0
	v_and_b32_e32 v0, 0xffffffc0, v35
	v_sub_u32_e32 v66, v112, v0
	v_mov_b32_e32 v0, v117
	v_cmp_lt_i32_e64 s[4:5], 0, v66
	v_ashrrev_i32_e32 v34, 4, v0
	v_and_b32_e32 v88, 15, v0
	s_waitcnt lgkmcnt(0)
	v_lshlrev_b64 v[0:1], 15, v[112:113]
	v_lshlrev_b32_e32 v64, 3, v34
	v_lshl_add_u64 v[0:1], s[18:19], 0, v[0:1]
	v_ashrrev_i32_e32 v65, 31, v64
	v_lshl_add_u64 v[0:1], v[64:65], 2, v[0:1]
	v_lshlrev_b32_e32 v114, 8, v88
	v_lshl_add_u64 v[0:1], v[0:1], 0, v[114:115]
	v_lshl_add_u64 v[32:33], v[0:1], 0, s[38:39]
	s_and_saveexec_b64 s[0:1], s[4:5]
	s_cbranch_execz .Lp7_pf_done
	v_mov_b32_e32 v202, 0x1000
	v_mov_b32_e32 v203, 0
	global_load_dwordx4 v[204:207], v[32:33], off
	global_load_dwordx4 v[204:207], v[32:33], off offset:128
	v_lshl_add_u64 v[200:201], v[32:33], 0, v[202:203]
	global_load_dwordx4 v[204:207], v[200:201], off
	global_load_dwordx4 v[204:207], v[200:201], off offset:128
	v_lshl_add_u64 v[200:201], v[200:201], 0, v[202:203]
	global_load_dwordx4 v[204:207], v[200:201], off
	global_load_dwordx4 v[204:207], v[200:201], off offset:128
	v_lshl_add_u64 v[200:201], v[200:201], 0, v[202:203]
	global_load_dwordx4 v[204:207], v[200:201], off
	global_load_dwordx4 v[204:207], v[200:201], off offset:128
.Lp7_pf_done:
	s_or_b64 exec, exec, s[0:1]
	v_mov_b32_e32 v0, v115
	v_mov_b32_e32 v1, v115
	v_mov_b32_e32 v2, v115
	v_mov_b32_e32 v3, v115
	s_and_saveexec_b64 s[0:1], s[4:5]
	s_cbranch_execz .LBB0_1353
	global_load_dwordx4 v[0:3], v[32:33], off
	global_load_dwordx4 v[4:7], v[32:33], off offset:16
	s_waitcnt vmcnt(0)
	v_bfe_u32 v8, v0, 16, 1
	v_bfe_u32 v10, v2, 16, 1
	v_bfe_u32 v12, v4, 16, 1
	v_bfe_u32 v14, v6, 16, 1
	v_bfe_u32 v9, v1, 16, 1
	v_bfe_u32 v11, v3, 16, 1
	v_bfe_u32 v13, v5, 16, 1
	v_bfe_u32 v15, v7, 16, 1
	v_add3_u32 v0, v0, v8, s33
	v_add3_u32 v2, v2, v10, s33
	v_add3_u32 v4, v4, v12, s33
	v_add3_u32 v6, v6, v14, s33
	v_add3_u32 v1, v1, v9, s33
	v_add3_u32 v3, v3, v11, s33
	v_add3_u32 v5, v5, v13, s33
	v_add3_u32 v7, v7, v15, s33
	v_lshrrev_b32_e32 v0, 16, v0
	v_lshrrev_b32_e32 v2, 16, v2
	v_lshrrev_b32_e32 v4, 16, v4
	v_lshrrev_b32_e32 v6, 16, v6
	v_and_or_b32 v0, v1, s50, v0
	v_and_or_b32 v1, v3, s50, v2
	v_and_or_b32 v2, v5, s50, v4
	v_and_or_b32 v3, v7, s50, v6
